# mode-1 attention epilogue: batched gate+park loads (32 in flight), counted vmcnt
# speedup vs baseline: 1.0329x; 1.0198x over previous
; __device__ __forceinline__ float bf2f(bf16_t v) { return __uint_as_float(((unsigned)v) << 16); }
; __device__ __forceinline__ int crow(int r, int hi) { return (r & 3) + 8 * (r >> 2) + 4 * hi; }
; template <int MODE>
; __device__ __forceinline__ void attn_body(const bf16_t* __restrict__ Qb, const bf16_t* __restrict__ Kh, const bf16_t* __restrict__ Vh, int NT, int krel0,
;                                           char* lds, const float* __restrict__ lutg, const AttnEpi& E) {
;     ...
;   if (hi == 0) li_l[r32] = l_reg; asm volatile("s_waitcnt lgkmcnt(0)" ::: "memory");
;   float rli[16];
; #pragma unroll
;   for (int r = 0; r < 16; ++r) rli[r] = __builtin_amdgcn_rcpf(li_l[crow(r, hi)]);
;   float* pk0 = E.park; float* pk1 = E.park + 64 * 512;
;   const int rowb = wid * 32;
;   if constexpr (MODE == 0 || MODE == 1) {
; #pragma unroll
;     for (int r = 0; r < 16; ++r) { const int row = rowb + crow(r, hi);
; #pragma unroll
;       for (int d0 = 0; d0 < 4; ++d0) { const int idx = (d0 * 16 + r) * 512 + tid;
;         const float g = bf2f(E.gate[(size_t)row * GW + d0 * 32 + r32]);
;         const float v = o[d0][r] * rli[r] * g;
;         if constexpr (MODE == 0) pk0[idx] = v; else pk0[idx] += v; } }
.LBB0_123:
	s_or_b64 exec, exec, s[0:1]
	s_waitcnt lgkmcnt(0)
	ds_read_b128 v[66:69], v209
	ds_read_b128 v[70:73], v209 offset:32
	v_lshlrev_b32_e32 v0, 1, v204
	s_add_u32 s60, s58, 0x2060
	s_addc_u32 s61, s59, 0
	s_waitcnt lgkmcnt(1)
	v_rcp_f32_e32 v88, v66
	v_rcp_f32_e32 v89, v67
	v_rcp_f32_e32 v81, v68
	v_rcp_f32_e32 v80, v69
	ds_read_b128 v[66:69], v209 offset:64
	ds_read_b128 v[82:85], v209 offset:96
	s_waitcnt lgkmcnt(2)
	v_rcp_f32_e32 v79, v70
	v_rcp_f32_e32 v78, v71
	v_rcp_f32_e32 v77, v72
	s_waitcnt lgkmcnt(1)
	v_rcp_f32_e32 v75, v66
	v_rcp_f32_e32 v74, v67
	v_lshl_add_u64 v[66:67], s[56:57], 0, v[0:1]
	v_or_b32_e32 v0, v205, v108
	s_waitcnt lgkmcnt(0)
	v_rcp_f32_e32 v71, v82
	v_rcp_f32_e32 v70, v83
	v_rcp_f32_e32 v72, v69
	v_rcp_f32_e32 v69, v84
	v_rcp_f32_e32 v76, v73
	v_rcp_f32_e32 v73, v68
	v_rcp_f32_e32 v68, v85
	v_lshlrev_b32_e32 v134, 2, v188
	s_add_u32 s20, s34, 0x0
	s_addc_u32 s21, s35, 0
	s_add_u32 s22, s34, 0x8000
	s_addc_u32 s23, s35, 0
	s_add_u32 s24, s34, 0x10000
	s_addc_u32 s25, s35, 0
	s_add_u32 s26, s34, 0x18000
	s_addc_u32 s27, s35, 0
	v_mad_i64_i32 v[130:131], s[28:29], v0, s88, v[66:67]
	global_load_ushort v98, v[130:131], off offset:2048
	global_load_dword v114, v134, s[20:21]
	global_load_ushort v99, v[130:131], off offset:2112
	global_load_dword v115, v134, s[22:23]
	global_load_ushort v100, v[130:131], off offset:2176
	global_load_dword v116, v134, s[24:25]
	global_load_ushort v101, v[130:131], off offset:2240
	global_load_dword v117, v134, s[26:27]
	v_or_b32_e32 v132, 1, v0
	v_mad_i64_i32 v[130:131], s[28:29], v132, s88, v[66:67]
	global_load_ushort v102, v[130:131], off offset:2048
	global_load_dword v118, v134, s[20:21] offset:2048
	global_load_ushort v103, v[130:131], off offset:2112
	global_load_dword v119, v134, s[22:23] offset:2048
	global_load_ushort v104, v[130:131], off offset:2176
	global_load_dword v120, v134, s[24:25] offset:2048
	global_load_ushort v105, v[130:131], off offset:2240
	global_load_dword v121, v134, s[26:27] offset:2048
	s_add_u32 s20, s34, 0x1000
	s_addc_u32 s21, s35, 0
	s_add_u32 s22, s34, 0x9000
	s_addc_u32 s23, s35, 0
	s_add_u32 s24, s34, 0x11000
	s_addc_u32 s25, s35, 0
	s_add_u32 s26, s34, 0x19000
	s_addc_u32 s27, s35, 0
	v_or_b32_e32 v132, 2, v0
	v_mad_i64_i32 v[130:131], s[28:29], v132, s88, v[66:67]
	global_load_ushort v106, v[130:131], off offset:2048
	global_load_dword v122, v134, s[20:21]
	global_load_ushort v107, v[130:131], off offset:2112
	global_load_dword v123, v134, s[22:23]
	global_load_ushort v108, v[130:131], off offset:2176
	global_load_dword v124, v134, s[24:25]
	global_load_ushort v109, v[130:131], off offset:2240
	global_load_dword v125, v134, s[26:27]
	v_or_b32_e32 v132, 3, v0
	v_mad_i64_i32 v[130:131], s[28:29], v132, s88, v[66:67]
	global_load_ushort v110, v[130:131], off offset:2048
	global_load_dword v126, v134, s[20:21] offset:2048
	global_load_ushort v111, v[130:131], off offset:2112
	global_load_dword v127, v134, s[22:23] offset:2048
	global_load_ushort v112, v[130:131], off offset:2176
	global_load_dword v128, v134, s[24:25] offset:2048
	global_load_ushort v113, v[130:131], off offset:2240
	global_load_dword v129, v134, s[26:27] offset:2048
	s_add_u32 s20, s34, 0x0
	s_addc_u32 s21, s35, 0
	s_add_u32 s22, s34, 0x8000
	s_addc_u32 s23, s35, 0
	s_add_u32 s24, s34, 0x10000
	s_addc_u32 s25, s35, 0
	s_add_u32 s26, s34, 0x18000
	s_addc_u32 s27, s35, 0
	s_waitcnt vmcnt(30)
	v_lshlrev_b32_e32 v98, 16, v98
	v_mul_f32_e32 v50, v50, v88
	v_fmac_f32_e32 v114, v50, v98
	global_store_dword v134, v114, s[20:21]
	s_waitcnt vmcnt(29)
	v_lshlrev_b32_e32 v99, 16, v99
	v_mul_f32_e32 v34, v34, v88
	v_fmac_f32_e32 v115, v34, v99
	global_store_dword v134, v115, s[22:23]
	s_waitcnt vmcnt(28)
	v_lshlrev_b32_e32 v100, 16, v100
	v_mul_f32_e32 v18, v18, v88
	v_fmac_f32_e32 v116, v18, v100
	global_store_dword v134, v116, s[24:25]
	s_waitcnt vmcnt(27)
	v_lshlrev_b32_e32 v101, 16, v101
	v_mul_f32_e32 v2, v2, v88
	v_fmac_f32_e32 v117, v2, v101
	global_store_dword v134, v117, s[26:27]
	s_waitcnt vmcnt(26)
	v_lshlrev_b32_e32 v102, 16, v102
	v_mul_f32_e32 v51, v51, v89
	v_fmac_f32_e32 v118, v51, v102
	global_store_dword v134, v118, s[20:21] offset:2048
	s_waitcnt vmcnt(25)
	v_lshlrev_b32_e32 v103, 16, v103
	v_mul_f32_e32 v35, v35, v89
	v_fmac_f32_e32 v119, v35, v103
	global_store_dword v134, v119, s[22:23] offset:2048
	s_waitcnt vmcnt(24)
	v_lshlrev_b32_e32 v104, 16, v104
	v_mul_f32_e32 v19, v19, v89
	v_fmac_f32_e32 v120, v19, v104
	global_store_dword v134, v120, s[24:25] offset:2048
	s_waitcnt vmcnt(23)
	v_lshlrev_b32_e32 v105, 16, v105
	v_mul_f32_e32 v3, v3, v89
	v_fmac_f32_e32 v121, v3, v105
	global_store_dword v134, v121, s[26:27] offset:2048
	s_add_u32 s20, s34, 0x1000
	s_addc_u32 s21, s35, 0
	s_add_u32 s22, s34, 0x9000
	s_addc_u32 s23, s35, 0
	s_add_u32 s24, s34, 0x11000
	s_addc_u32 s25, s35, 0
	s_add_u32 s26, s34, 0x19000
	s_addc_u32 s27, s35, 0
	s_waitcnt vmcnt(22)
	v_lshlrev_b32_e32 v106, 16, v106
	v_mul_f32_e32 v52, v52, v81
	v_fmac_f32_e32 v122, v52, v106
	global_store_dword v134, v122, s[20:21]
	s_waitcnt vmcnt(21)
	v_lshlrev_b32_e32 v107, 16, v107
	v_mul_f32_e32 v36, v36, v81
	v_fmac_f32_e32 v123, v36, v107
	global_store_dword v134, v123, s[22:23]
	s_waitcnt vmcnt(20)
	v_lshlrev_b32_e32 v108, 16, v108
	v_mul_f32_e32 v20, v20, v81
	v_fmac_f32_e32 v124, v20, v108
	global_store_dword v134, v124, s[24:25]
	s_waitcnt vmcnt(19)
	v_lshlrev_b32_e32 v109, 16, v109
	v_mul_f32_e32 v4, v4, v81
	v_fmac_f32_e32 v125, v4, v109
	global_store_dword v134, v125, s[26:27]
	s_waitcnt vmcnt(18)
	v_lshlrev_b32_e32 v110, 16, v110
	v_mul_f32_e32 v53, v53, v80
	v_fmac_f32_e32 v126, v53, v110
	global_store_dword v134, v126, s[20:21] offset:2048
	s_waitcnt vmcnt(17)
; __device__ __forceinline__ float bf2f(bf16_t v) { return __uint_as_float(((unsigned)v) << 16); }
; __device__ __forceinline__ int crow(int r, int hi) { return (r & 3) + 8 * (r >> 2) + 4 * hi; }
; template <int MODE>
; __device__ __forceinline__ void attn_body(const bf16_t* __restrict__ Qb, const bf16_t* __restrict__ Kh, const bf16_t* __restrict__ Vh, int NT, int krel0,
;                                           char* lds, const float* __restrict__ lutg, const AttnEpi& E) {
;     ...
;   if constexpr (MODE == 0 || MODE == 1) {
; #pragma unroll
;     for (int r = 0; r < 16; ++r) { const int row = rowb + crow(r, hi);
; #pragma unroll
;       for (int d0 = 0; d0 < 4; ++d0) { const int idx = (d0 * 16 + r) * 512 + tid;
;         const float g = bf2f(E.gate[(size_t)row * GW + d0 * 32 + r32]);
;         const float v = o[d0][r] * rli[r] * g;
;         if constexpr (MODE == 0) pk0[idx] = v; else pk0[idx] += v; } }
	v_lshlrev_b32_e32 v111, 16, v111
	v_mul_f32_e32 v37, v37, v80
	v_fmac_f32_e32 v127, v37, v111
	global_store_dword v134, v127, s[22:23] offset:2048
	s_waitcnt vmcnt(16)
	v_lshlrev_b32_e32 v112, 16, v112
	v_mul_f32_e32 v21, v21, v80
	v_fmac_f32_e32 v128, v21, v112
	global_store_dword v134, v128, s[24:25] offset:2048
	s_waitcnt vmcnt(15)
	v_lshlrev_b32_e32 v113, 16, v113
	v_mul_f32_e32 v5, v5, v80
	v_fmac_f32_e32 v129, v5, v113
	global_store_dword v134, v129, s[26:27] offset:2048
	s_add_u32 s20, s34, 0x2000
	s_addc_u32 s21, s35, 0
	s_add_u32 s22, s34, 0xa000
	s_addc_u32 s23, s35, 0
	s_add_u32 s24, s34, 0x12000
	s_addc_u32 s25, s35, 0
	s_add_u32 s26, s34, 0x1a000
	s_addc_u32 s27, s35, 0
	v_or_b32_e32 v132, 8, v0
	v_mad_i64_i32 v[130:131], s[28:29], v132, s88, v[66:67]
	global_load_ushort v136, v[130:131], off offset:2048
	global_load_dword v152, v134, s[20:21]
	global_load_ushort v137, v[130:131], off offset:2112
	global_load_dword v153, v134, s[22:23]
	global_load_ushort v138, v[130:131], off offset:2176
	global_load_dword v154, v134, s[24:25]
	global_load_ushort v139, v[130:131], off offset:2240
	global_load_dword v155, v134, s[26:27]
	v_or_b32_e32 v132, 9, v0
	v_mad_i64_i32 v[130:131], s[28:29], v132, s88, v[66:67]
	global_load_ushort v140, v[130:131], off offset:2048
	global_load_dword v156, v134, s[20:21] offset:2048
	global_load_ushort v141, v[130:131], off offset:2112
	global_load_dword v157, v134, s[22:23] offset:2048
	global_load_ushort v142, v[130:131], off offset:2176
	global_load_dword v158, v134, s[24:25] offset:2048
	global_load_ushort v143, v[130:131], off offset:2240
	global_load_dword v159, v134, s[26:27] offset:2048
	s_add_u32 s20, s34, 0x3000
	s_addc_u32 s21, s35, 0
	s_add_u32 s22, s34, 0xb000
	s_addc_u32 s23, s35, 0
	s_add_u32 s24, s34, 0x13000
	s_addc_u32 s25, s35, 0
	s_add_u32 s26, s34, 0x1b000
	s_addc_u32 s27, s35, 0
	v_or_b32_e32 v132, 10, v0
	v_mad_i64_i32 v[130:131], s[28:29], v132, s88, v[66:67]
	global_load_ushort v144, v[130:131], off offset:2048
	global_load_dword v160, v134, s[20:21]
	global_load_ushort v145, v[130:131], off offset:2112
	global_load_dword v161, v134, s[22:23]
	global_load_ushort v146, v[130:131], off offset:2176
	global_load_dword v162, v134, s[24:25]
	global_load_ushort v147, v[130:131], off offset:2240
	global_load_dword v163, v134, s[26:27]
	v_or_b32_e32 v132, 11, v0
	v_mad_i64_i32 v[130:131], s[28:29], v132, s88, v[66:67]
	global_load_ushort v148, v[130:131], off offset:2048
	global_load_dword v164, v134, s[20:21] offset:2048
	global_load_ushort v149, v[130:131], off offset:2112
	global_load_dword v165, v134, s[22:23] offset:2048
	global_load_ushort v150, v[130:131], off offset:2176
	global_load_dword v166, v134, s[24:25] offset:2048
	global_load_ushort v151, v[130:131], off offset:2240
	global_load_dword v167, v134, s[26:27] offset:2048
	s_add_u32 s20, s34, 0x2000
	s_addc_u32 s21, s35, 0
	s_add_u32 s22, s34, 0xa000
	s_addc_u32 s23, s35, 0
	s_add_u32 s24, s34, 0x12000
	s_addc_u32 s25, s35, 0
	s_add_u32 s26, s34, 0x1a000
	s_addc_u32 s27, s35, 0
	s_waitcnt vmcnt(30)
	v_lshlrev_b32_e32 v136, 16, v136
	v_mul_f32_e32 v54, v54, v79
	v_fmac_f32_e32 v152, v54, v136
	global_store_dword v134, v152, s[20:21]
	s_waitcnt vmcnt(29)
	v_lshlrev_b32_e32 v137, 16, v137
	v_mul_f32_e32 v38, v38, v79
	v_fmac_f32_e32 v153, v38, v137
	global_store_dword v134, v153, s[22:23]
	s_waitcnt vmcnt(28)
	v_lshlrev_b32_e32 v138, 16, v138
	v_mul_f32_e32 v22, v22, v79
	v_fmac_f32_e32 v154, v22, v138
	global_store_dword v134, v154, s[24:25]
	s_waitcnt vmcnt(27)
	v_lshlrev_b32_e32 v139, 16, v139
	v_mul_f32_e32 v6, v6, v79
	v_fmac_f32_e32 v155, v6, v139
	global_store_dword v134, v155, s[26:27]
	s_waitcnt vmcnt(26)
	v_lshlrev_b32_e32 v140, 16, v140
	v_mul_f32_e32 v55, v55, v78
	v_fmac_f32_e32 v156, v55, v140
	global_store_dword v134, v156, s[20:21] offset:2048
	s_waitcnt vmcnt(25)
	v_lshlrev_b32_e32 v141, 16, v141
	v_mul_f32_e32 v39, v39, v78
	v_fmac_f32_e32 v157, v39, v141
	global_store_dword v134, v157, s[22:23] offset:2048
	s_waitcnt vmcnt(24)
	v_lshlrev_b32_e32 v142, 16, v142
	v_mul_f32_e32 v23, v23, v78
	v_fmac_f32_e32 v158, v23, v142
	global_store_dword v134, v158, s[24:25] offset:2048
	s_waitcnt vmcnt(23)
	v_lshlrev_b32_e32 v143, 16, v143
	v_mul_f32_e32 v7, v7, v78
	v_fmac_f32_e32 v159, v7, v143
	global_store_dword v134, v159, s[26:27] offset:2048
	s_add_u32 s20, s34, 0x3000
	s_addc_u32 s21, s35, 0
	s_add_u32 s22, s34, 0xb000
	s_addc_u32 s23, s35, 0
	s_add_u32 s24, s34, 0x13000
	s_addc_u32 s25, s35, 0
	s_add_u32 s26, s34, 0x1b000
	s_addc_u32 s27, s35, 0
	s_waitcnt vmcnt(22)
	v_lshlrev_b32_e32 v144, 16, v144
	v_mul_f32_e32 v56, v56, v77
	v_fmac_f32_e32 v160, v56, v144
	global_store_dword v134, v160, s[20:21]
	s_waitcnt vmcnt(21)
	v_lshlrev_b32_e32 v145, 16, v145
	v_mul_f32_e32 v40, v40, v77
	v_fmac_f32_e32 v161, v40, v145
	global_store_dword v134, v161, s[22:23]
	s_waitcnt vmcnt(20)
	v_lshlrev_b32_e32 v146, 16, v146
	v_mul_f32_e32 v24, v24, v77
	v_fmac_f32_e32 v162, v24, v146
	global_store_dword v134, v162, s[24:25]
	s_waitcnt vmcnt(19)
	v_lshlrev_b32_e32 v147, 16, v147
	v_mul_f32_e32 v8, v8, v77
	v_fmac_f32_e32 v163, v8, v147
	global_store_dword v134, v163, s[26:27]
	s_waitcnt vmcnt(18)
	v_lshlrev_b32_e32 v148, 16, v148
	v_mul_f32_e32 v57, v57, v76
	v_fmac_f32_e32 v164, v57, v148
	global_store_dword v134, v164, s[20:21] offset:2048
	s_waitcnt vmcnt(17)
	v_lshlrev_b32_e32 v149, 16, v149
	v_mul_f32_e32 v41, v41, v76
	v_fmac_f32_e32 v165, v41, v149
	global_store_dword v134, v165, s[22:23] offset:2048
	s_waitcnt vmcnt(16)
	v_lshlrev_b32_e32 v150, 16, v150
	v_mul_f32_e32 v25, v25, v76
	v_fmac_f32_e32 v166, v25, v150
	global_store_dword v134, v166, s[24:25] offset:2048
	s_waitcnt vmcnt(15)
; __device__ __forceinline__ float bf2f(bf16_t v) { return __uint_as_float(((unsigned)v) << 16); }
; __device__ __forceinline__ int crow(int r, int hi) { return (r & 3) + 8 * (r >> 2) + 4 * hi; }
; template <int MODE>
; __device__ __forceinline__ void attn_body(const bf16_t* __restrict__ Qb, const bf16_t* __restrict__ Kh, const bf16_t* __restrict__ Vh, int NT, int krel0,
;                                           char* lds, const float* __restrict__ lutg, const AttnEpi& E) {
;     ...
;   if constexpr (MODE == 0 || MODE == 1) {
; #pragma unroll
;     for (int r = 0; r < 16; ++r) { const int row = rowb + crow(r, hi);
; #pragma unroll
;       for (int d0 = 0; d0 < 4; ++d0) { const int idx = (d0 * 16 + r) * 512 + tid;
;         const float g = bf2f(E.gate[(size_t)row * GW + d0 * 32 + r32]);
;         const float v = o[d0][r] * rli[r] * g;
;         if constexpr (MODE == 0) pk0[idx] = v; else pk0[idx] += v; } }
	v_lshlrev_b32_e32 v151, 16, v151
	v_mul_f32_e32 v9, v9, v76
	v_fmac_f32_e32 v167, v9, v151
	global_store_dword v134, v167, s[26:27] offset:2048
	s_add_u32 s20, s34, 0x4000
	s_addc_u32 s21, s35, 0
	s_add_u32 s22, s34, 0xc000
	s_addc_u32 s23, s35, 0
	s_add_u32 s24, s34, 0x14000
	s_addc_u32 s25, s35, 0
	s_add_u32 s26, s34, 0x1c000
	s_addc_u32 s27, s35, 0
	v_or_b32_e32 v132, 16, v0
	v_mad_i64_i32 v[130:131], s[28:29], v132, s88, v[66:67]
	global_load_ushort v98, v[130:131], off offset:2048
	global_load_dword v114, v134, s[20:21]
	global_load_ushort v99, v[130:131], off offset:2112
	global_load_dword v115, v134, s[22:23]
	global_load_ushort v100, v[130:131], off offset:2176
	global_load_dword v116, v134, s[24:25]
	global_load_ushort v101, v[130:131], off offset:2240
	global_load_dword v117, v134, s[26:27]
	v_or_b32_e32 v132, 17, v0
	v_mad_i64_i32 v[130:131], s[28:29], v132, s88, v[66:67]
	global_load_ushort v102, v[130:131], off offset:2048
	global_load_dword v118, v134, s[20:21] offset:2048
	global_load_ushort v103, v[130:131], off offset:2112
	global_load_dword v119, v134, s[22:23] offset:2048
	global_load_ushort v104, v[130:131], off offset:2176
	global_load_dword v120, v134, s[24:25] offset:2048
	global_load_ushort v105, v[130:131], off offset:2240
	global_load_dword v121, v134, s[26:27] offset:2048
	s_add_u32 s20, s34, 0x5000
	s_addc_u32 s21, s35, 0
	s_add_u32 s22, s34, 0xd000
	s_addc_u32 s23, s35, 0
	s_add_u32 s24, s34, 0x15000
	s_addc_u32 s25, s35, 0
	s_add_u32 s26, s34, 0x1d000
	s_addc_u32 s27, s35, 0
	v_or_b32_e32 v132, 18, v0
	v_mad_i64_i32 v[130:131], s[28:29], v132, s88, v[66:67]
	global_load_ushort v106, v[130:131], off offset:2048
	global_load_dword v122, v134, s[20:21]
	global_load_ushort v107, v[130:131], off offset:2112
	global_load_dword v123, v134, s[22:23]
	global_load_ushort v108, v[130:131], off offset:2176
	global_load_dword v124, v134, s[24:25]
	global_load_ushort v109, v[130:131], off offset:2240
	global_load_dword v125, v134, s[26:27]
	v_or_b32_e32 v132, 19, v0
	v_mad_i64_i32 v[130:131], s[28:29], v132, s88, v[66:67]
	global_load_ushort v110, v[130:131], off offset:2048
	global_load_dword v126, v134, s[20:21] offset:2048
	global_load_ushort v111, v[130:131], off offset:2112
	global_load_dword v127, v134, s[22:23] offset:2048
	global_load_ushort v112, v[130:131], off offset:2176
	global_load_dword v128, v134, s[24:25] offset:2048
	global_load_ushort v113, v[130:131], off offset:2240
	global_load_dword v129, v134, s[26:27] offset:2048
	s_add_u32 s20, s34, 0x4000
	s_addc_u32 s21, s35, 0
	s_add_u32 s22, s34, 0xc000
	s_addc_u32 s23, s35, 0
	s_add_u32 s24, s34, 0x14000
	s_addc_u32 s25, s35, 0
	s_add_u32 s26, s34, 0x1c000
	s_addc_u32 s27, s35, 0
	s_waitcnt vmcnt(30)
	v_lshlrev_b32_e32 v98, 16, v98
	v_mul_f32_e32 v58, v58, v75
	v_fmac_f32_e32 v114, v58, v98
	global_store_dword v134, v114, s[20:21]
	s_waitcnt vmcnt(29)
	v_lshlrev_b32_e32 v99, 16, v99
	v_mul_f32_e32 v42, v42, v75
	v_fmac_f32_e32 v115, v42, v99
	global_store_dword v134, v115, s[22:23]
	s_waitcnt vmcnt(28)
	v_lshlrev_b32_e32 v100, 16, v100
	v_mul_f32_e32 v26, v26, v75
	v_fmac_f32_e32 v116, v26, v100
	global_store_dword v134, v116, s[24:25]
	s_waitcnt vmcnt(27)
	v_lshlrev_b32_e32 v101, 16, v101
	v_mul_f32_e32 v10, v10, v75
	v_fmac_f32_e32 v117, v10, v101
	global_store_dword v134, v117, s[26:27]
	s_waitcnt vmcnt(26)
	v_lshlrev_b32_e32 v102, 16, v102
	v_mul_f32_e32 v59, v59, v74
	v_fmac_f32_e32 v118, v59, v102
	global_store_dword v134, v118, s[20:21] offset:2048
	s_waitcnt vmcnt(25)
	v_lshlrev_b32_e32 v103, 16, v103
	v_mul_f32_e32 v43, v43, v74
	v_fmac_f32_e32 v119, v43, v103
	global_store_dword v134, v119, s[22:23] offset:2048
	s_waitcnt vmcnt(24)
	v_lshlrev_b32_e32 v104, 16, v104
	v_mul_f32_e32 v27, v27, v74
	v_fmac_f32_e32 v120, v27, v104
	global_store_dword v134, v120, s[24:25] offset:2048
	s_waitcnt vmcnt(23)
	v_lshlrev_b32_e32 v105, 16, v105
	v_mul_f32_e32 v11, v11, v74
	v_fmac_f32_e32 v121, v11, v105
	global_store_dword v134, v121, s[26:27] offset:2048
	s_add_u32 s20, s34, 0x5000
	s_addc_u32 s21, s35, 0
	s_add_u32 s22, s34, 0xd000
	s_addc_u32 s23, s35, 0
	s_add_u32 s24, s34, 0x15000
	s_addc_u32 s25, s35, 0
	s_add_u32 s26, s34, 0x1d000
	s_addc_u32 s27, s35, 0
	s_waitcnt vmcnt(22)
	v_lshlrev_b32_e32 v106, 16, v106
	v_mul_f32_e32 v60, v60, v73
	v_fmac_f32_e32 v122, v60, v106
	global_store_dword v134, v122, s[20:21]
	s_waitcnt vmcnt(21)
	v_lshlrev_b32_e32 v107, 16, v107
	v_mul_f32_e32 v44, v44, v73
	v_fmac_f32_e32 v123, v44, v107
	global_store_dword v134, v123, s[22:23]
	s_waitcnt vmcnt(20)
	v_lshlrev_b32_e32 v108, 16, v108
	v_mul_f32_e32 v28, v28, v73
	v_fmac_f32_e32 v124, v28, v108
	global_store_dword v134, v124, s[24:25]
	s_waitcnt vmcnt(19)
	v_lshlrev_b32_e32 v109, 16, v109
	v_mul_f32_e32 v12, v12, v73
	v_fmac_f32_e32 v125, v12, v109
	global_store_dword v134, v125, s[26:27]
	s_waitcnt vmcnt(18)
	v_lshlrev_b32_e32 v110, 16, v110
	v_mul_f32_e32 v61, v61, v72
	v_fmac_f32_e32 v126, v61, v110
	global_store_dword v134, v126, s[20:21] offset:2048
	s_waitcnt vmcnt(17)
	v_lshlrev_b32_e32 v111, 16, v111
	v_mul_f32_e32 v45, v45, v72
	v_fmac_f32_e32 v127, v45, v111
	global_store_dword v134, v127, s[22:23] offset:2048
	s_waitcnt vmcnt(16)
	v_lshlrev_b32_e32 v112, 16, v112
	v_mul_f32_e32 v29, v29, v72
	v_fmac_f32_e32 v128, v29, v112
	global_store_dword v134, v128, s[24:25] offset:2048
	s_waitcnt vmcnt(15)
; __device__ __forceinline__ float bf2f(bf16_t v) { return __uint_as_float(((unsigned)v) << 16); }
; __device__ __forceinline__ int crow(int r, int hi) { return (r & 3) + 8 * (r >> 2) + 4 * hi; }
; template <int MODE>
; __device__ __forceinline__ void attn_body(const bf16_t* __restrict__ Qb, const bf16_t* __restrict__ Kh, const bf16_t* __restrict__ Vh, int NT, int krel0,
;                                           char* lds, const float* __restrict__ lutg, const AttnEpi& E) {
;     ...
;   __syncthreads();
;   if constexpr (MODE != 0) { if (tid < 259) lut[tid] = lutg[tid]; }
;     ...
;   if constexpr (MODE == 0 || MODE == 1) {
; #pragma unroll
;     for (int r = 0; r < 16; ++r) { const int row = rowb + crow(r, hi);
; #pragma unroll
;       for (int d0 = 0; d0 < 4; ++d0) { const int idx = (d0 * 16 + r) * 512 + tid;
;         const float g = bf2f(E.gate[(size_t)row * GW + d0 * 32 + r32]);
;         const float v = o[d0][r] * rli[r] * g;
;         if constexpr (MODE == 0) pk0[idx] = v; else pk0[idx] += v; } }
	v_lshlrev_b32_e32 v113, 16, v113
	v_mul_f32_e32 v13, v13, v72
	v_fmac_f32_e32 v129, v13, v113
	global_store_dword v134, v129, s[26:27] offset:2048
	s_add_u32 s20, s34, 0x6000
	s_addc_u32 s21, s35, 0
	s_add_u32 s22, s34, 0xe000
	s_addc_u32 s23, s35, 0
	s_add_u32 s24, s34, 0x16000
	s_addc_u32 s25, s35, 0
	s_add_u32 s26, s34, 0x1e000
	s_addc_u32 s27, s35, 0
	v_or_b32_e32 v132, 24, v0
	v_mad_i64_i32 v[130:131], s[28:29], v132, s88, v[66:67]
	global_load_ushort v136, v[130:131], off offset:2048
	global_load_dword v152, v134, s[20:21]
	global_load_ushort v137, v[130:131], off offset:2112
	global_load_dword v153, v134, s[22:23]
	global_load_ushort v138, v[130:131], off offset:2176
	global_load_dword v154, v134, s[24:25]
	global_load_ushort v139, v[130:131], off offset:2240
	global_load_dword v155, v134, s[26:27]
	v_or_b32_e32 v132, 25, v0
	v_mad_i64_i32 v[130:131], s[28:29], v132, s88, v[66:67]
	global_load_ushort v140, v[130:131], off offset:2048
	global_load_dword v156, v134, s[20:21] offset:2048
	global_load_ushort v141, v[130:131], off offset:2112
	global_load_dword v157, v134, s[22:23] offset:2048
	global_load_ushort v142, v[130:131], off offset:2176
	global_load_dword v158, v134, s[24:25] offset:2048
	global_load_ushort v143, v[130:131], off offset:2240
	global_load_dword v159, v134, s[26:27] offset:2048
	s_add_u32 s20, s34, 0x7000
	s_addc_u32 s21, s35, 0
	s_add_u32 s22, s34, 0xf000
	s_addc_u32 s23, s35, 0
	s_add_u32 s24, s34, 0x17000
	s_addc_u32 s25, s35, 0
	s_add_u32 s26, s34, 0x1f000
	s_addc_u32 s27, s35, 0
	v_or_b32_e32 v132, 26, v0
	v_mad_i64_i32 v[130:131], s[28:29], v132, s88, v[66:67]
	global_load_ushort v144, v[130:131], off offset:2048
	global_load_dword v160, v134, s[20:21]
	global_load_ushort v145, v[130:131], off offset:2112
	global_load_dword v161, v134, s[22:23]
	global_load_ushort v146, v[130:131], off offset:2176
	global_load_dword v162, v134, s[24:25]
	global_load_ushort v147, v[130:131], off offset:2240
	global_load_dword v163, v134, s[26:27]
	v_or_b32_e32 v132, 27, v0
	v_mad_i64_i32 v[130:131], s[28:29], v132, s88, v[66:67]
	global_load_ushort v148, v[130:131], off offset:2048
	global_load_dword v164, v134, s[20:21] offset:2048
	global_load_ushort v149, v[130:131], off offset:2112
	global_load_dword v165, v134, s[22:23] offset:2048
	global_load_ushort v150, v[130:131], off offset:2176
	global_load_dword v166, v134, s[24:25] offset:2048
	global_load_ushort v151, v[130:131], off offset:2240
	global_load_dword v167, v134, s[26:27] offset:2048
	s_add_u32 s20, s34, 0x6000
	s_addc_u32 s21, s35, 0
	s_add_u32 s22, s34, 0xe000
	s_addc_u32 s23, s35, 0
	s_add_u32 s24, s34, 0x16000
	s_addc_u32 s25, s35, 0
	s_add_u32 s26, s34, 0x1e000
	s_addc_u32 s27, s35, 0
	s_waitcnt vmcnt(30)
	v_lshlrev_b32_e32 v136, 16, v136
	v_mul_f32_e32 v62, v62, v71
	v_fmac_f32_e32 v152, v62, v136
	global_store_dword v134, v152, s[20:21]
	s_waitcnt vmcnt(29)
	v_lshlrev_b32_e32 v137, 16, v137
	v_mul_f32_e32 v46, v46, v71
	v_fmac_f32_e32 v153, v46, v137
	global_store_dword v134, v153, s[22:23]
	s_waitcnt vmcnt(28)
	v_lshlrev_b32_e32 v138, 16, v138
	v_mul_f32_e32 v30, v30, v71
	v_fmac_f32_e32 v154, v30, v138
	global_store_dword v134, v154, s[24:25]
	s_waitcnt vmcnt(27)
	v_lshlrev_b32_e32 v139, 16, v139
	v_mul_f32_e32 v14, v14, v71
	v_fmac_f32_e32 v155, v14, v139
	global_store_dword v134, v155, s[26:27]
	s_waitcnt vmcnt(26)
	v_lshlrev_b32_e32 v140, 16, v140
	v_mul_f32_e32 v63, v63, v70
	v_fmac_f32_e32 v156, v63, v140
	global_store_dword v134, v156, s[20:21] offset:2048
	s_waitcnt vmcnt(25)
	v_lshlrev_b32_e32 v141, 16, v141
	v_mul_f32_e32 v47, v47, v70
	v_fmac_f32_e32 v157, v47, v141
	global_store_dword v134, v157, s[22:23] offset:2048
	s_waitcnt vmcnt(24)
	v_lshlrev_b32_e32 v142, 16, v142
	v_mul_f32_e32 v31, v31, v70
	v_fmac_f32_e32 v158, v31, v142
	global_store_dword v134, v158, s[24:25] offset:2048
	s_waitcnt vmcnt(23)
	v_lshlrev_b32_e32 v143, 16, v143
	v_mul_f32_e32 v15, v15, v70
	v_fmac_f32_e32 v159, v15, v143
	global_store_dword v134, v159, s[26:27] offset:2048
	s_add_u32 s20, s34, 0x7000
	s_addc_u32 s21, s35, 0
	s_add_u32 s22, s34, 0xf000
	s_addc_u32 s23, s35, 0
	s_add_u32 s24, s34, 0x17000
	s_addc_u32 s25, s35, 0
	s_add_u32 s26, s34, 0x1f000
	s_addc_u32 s27, s35, 0
	s_waitcnt vmcnt(22)
	v_lshlrev_b32_e32 v144, 16, v144
	v_mul_f32_e32 v64, v64, v69
	v_fmac_f32_e32 v160, v64, v144
	global_store_dword v134, v160, s[20:21]
	s_waitcnt vmcnt(21)
	v_lshlrev_b32_e32 v145, 16, v145
	v_mul_f32_e32 v48, v48, v69
	v_fmac_f32_e32 v161, v48, v145
	global_store_dword v134, v161, s[22:23]
	s_waitcnt vmcnt(20)
	v_lshlrev_b32_e32 v146, 16, v146
	v_mul_f32_e32 v32, v32, v69
	v_fmac_f32_e32 v162, v32, v146
	global_store_dword v134, v162, s[24:25]
	s_waitcnt vmcnt(19)
	v_lshlrev_b32_e32 v147, 16, v147
	v_mul_f32_e32 v16, v16, v69
	v_fmac_f32_e32 v163, v16, v147
	global_store_dword v134, v163, s[26:27]
	s_waitcnt vmcnt(18)
	v_lshlrev_b32_e32 v148, 16, v148
	v_mul_f32_e32 v65, v65, v68
	v_fmac_f32_e32 v164, v65, v148
	global_store_dword v134, v164, s[20:21] offset:2048
	s_waitcnt vmcnt(17)
	v_lshlrev_b32_e32 v149, 16, v149
	v_mul_f32_e32 v49, v49, v68
	v_fmac_f32_e32 v165, v49, v149
	global_store_dword v134, v165, s[22:23] offset:2048
	s_waitcnt vmcnt(16)
	v_lshlrev_b32_e32 v150, 16, v150
	v_mul_f32_e32 v33, v33, v68
	v_fmac_f32_e32 v166, v33, v150
	global_store_dword v134, v166, s[24:25] offset:2048
	s_waitcnt vmcnt(15)
	v_lshlrev_b32_e32 v151, 16, v151
	v_mul_f32_e32 v17, v17, v68
	v_fmac_f32_e32 v167, v17, v151
	global_store_dword v134, v167, s[26:27] offset:2048
	s_movk_i32 s0, 0x103
	v_mov_b32_e32 v188, v179
	s_nop 0
	v_cmp_gt_i32_e32 vcc, s0, v188
	v_ashrrev_i32_e32 v189, 31, v188
	s_barrier
	s_and_saveexec_b64 s[0:1], vcc
	s_cbranch_execz .LBB0_125
	v_lshl_add_u64 v[2:3], v[188:189], 2, s[60:61]
	global_load_dword v2, v[2:3], off
	v_lshl_add_u32 v0, v188, 2, 0
	v_add_u32_e32 v0, 0x18800, v0
	s_waitcnt vmcnt(0)
	ds_write_b32 v0, v2
